# static s_setprio 1 for waves 0-3 (older half), per-phase flips deleted
# speedup vs baseline: 1.0139x; 1.0075x over previous
_Z10fwd_kernel4Args:
	s_load_dwordx2 s[12:13], s[0:1], 0x100
	s_add_u32 s74, s0, 0x100
	v_and_b32_e32 v218, 0x3ff, v0
	s_mov_b32 s97, s2
	s_addc_u32 s75, s1, 0
	s_mov_b64 s[4:5], s[0:1]
	v_readfirstlane_b32 s100, v0
	s_nop 3
	s_and_b32 s100, s100, 0x3ff
	s_lshr_b32 s100, s100, 6
	s_cmp_lt_u32 s100, 4
	s_cbranch_scc0 .Lprio_done
	s_setprio 1
